# P4 boundary-tile test made exact for the 8192-token sequences (tiles near a 4096 multiple that is not a sequence boundary take the fast path)
# speedup vs baseline: 1.0010x; 1.0010x over previous
;     __device__ __forceinline__ void operator()(f32x4 (&acc)[2][2][4][2], const Unit& u, int wr, int wc, int fr, int fq) const {
;     ...
;         const int tok0 = 254 * u.pm - 1;
;         const int pcol = wc * 32 + 8 * fq;
;         const bool bnd = (tok0 < 0) || (((tok0 & (SEQP - 1)) + 256) >= SEQP) || (tok0 + 256 > MTOK);
; #pragma unroll
;         for (int ai = 0; ai < 2; ++ai)
; #pragma unroll
;             for (int m = 0; m < 4; ++m) {
;                 const int tok = tok0 + ai * 128 + wr * 64 + m * 16 + fr;
;                 if (bnd) {
;                     const bool valid = (tok >= 0) && (tok < MTOK);
;                     float rs = 0.f; if (valid) rs = rsqrtf(rss[tok] * (1.0f / 1024.0f) + EPSV);
; #pragma unroll
;                     for (int bj = 0; bj < 2; ++bj)
; #pragma unroll
;                         for (int n = 0; n < 2; ++n) { f32x4 x = acc[ai][bj][m][n] * rs;
; #pragma unroll
;                             for (int j = 0; j < 4; ++j) x[j] = valid ? x[j] : 0.f;
;                             acc[ai][bj][m][n] = x; }
;                 } else {
;                     const float rs = rsqrtf(rss[tok] * (1.0f / 1024.0f) + EPSV);
; #pragma unroll
;                     for (int bj = 0; bj < 2; ++bj)
; #pragma unroll
;                         for (int n = 0; n < 2; ++n) acc[ai][bj][m][n] = acc[ai][bj][m][n] * rs;
;                 }
.LBB0_568:
	s_mul_i32 s36, s12, 0xfe
	s_add_i32 s4, s36, -1
	s_movk_i32 s5, 0xf00
	s_cmp_lt_i32 s4, 0x10000
	s_cselect_b32 s5, s5, 0x1f00
	s_and_b32 s0, s4, s5
	s_cmp_lg_u32 s0, s5
	s_cselect_b64 s[0:1], -1, 0
	s_add_i32 s5, s12, 0xfffffdfc
	s_cmp_gt_u32 s5, 0xfffffdfc
	v_mov_b32_e32 v190, v237
	v_mov_b32_e32 v228, v236
	s_cselect_b64 s[6:7], -1, 0
	s_and_b64 s[12:13], s[6:7], s[0:1]
	v_add_u32_e32 v245, s48, v228
	v_add_u32_e32 v152, s4, v245
	s_mov_b64 s[0:1], -1
	s_and_b64 vcc, exec, s[12:13]
	s_mov_b32 s93, s17
	s_cbranch_vccz .LBB0_570
	v_ashrrev_i32_e32 v1, 31, v152
	v_mov_b32_e32 v0, v152
	v_lshl_add_u64 v[0:1], v[0:1], 2, s[60:61]
	s_mov_b32 s0, 0x800000
	s_waitcnt vmcnt(0)
	v_mov_b32_e32 v0, v248
	v_fmamk_f32 v0, v0, 0x3a800000, v242
	v_mul_f32_e32 v1, 0x4b800000, v0
	v_cmp_gt_f32_e32 vcc, s0, v0
	s_mov_b64 s[0:1], 0
	s_nop 0
	v_cndmask_b32_e32 v0, v0, v1, vcc
	v_rsq_f32_e32 v0, v0
	s_nop 0
	v_mul_f32_e32 v1, 0x45800000, v0
	v_cndmask_b32_e32 v4, v0, v1, vcc
	v_pk_mul_f32 v[34:35], v[142:143], v[4:5] op_sel_hi:[1,0]
	v_pk_mul_f32 v[32:33], v[140:141], v[4:5] op_sel_hi:[1,0]
	v_pk_mul_f32 v[2:3], v[138:139], v[4:5] op_sel_hi:[1,0]
	v_pk_mul_f32 v[0:1], v[136:137], v[4:5] op_sel_hi:[1,0]
	v_pk_mul_f32 v[38:39], v[134:135], v[4:5] op_sel_hi:[1,0]
	v_pk_mul_f32 v[36:37], v[132:133], v[4:5] op_sel_hi:[1,0]
	v_pk_mul_f32 v[6:7], v[130:131], v[4:5] op_sel_hi:[1,0]
	v_pk_mul_f32 v[4:5], v[128:129], v[4:5] op_sel_hi:[1,0]
